# second QK step of each attention loop iteration issues its eight forget-bias LDS reads before the LDS-DMA issue block (first-consumer wait placement)
# baseline (speedup 1.0000x reference)
; __device__ __forceinline__ void qkt(f32x16& p0, f32x16& p1, const char* Kslot, int r32, int hi, const bf16x8* qr, const LAS f32x4* cp) {
;     ...
;     for (int g = 0; g < 4; ++g) { const f32x4 c0 = cp[2 * g], c1 = cp[8 + 2 * g];
; #pragma unroll
;         for (int j = 0; j < 4; ++j) { p0[4 * g + j] = c0[j]; p1[4 * g + j] = c1[j]; } }
.LBB0_533:
	s_add_i32 s2, s76, 0
	v_add_u32_e32 v237, s2, v193
	ds_read_b128 v[80:83], v217 offset:256
	ds_read_b128 v[84:87], v217 offset:288
	ds_read_b128 v[64:67], v217 offset:384
	ds_read_b128 v[68:71], v217 offset:416
	ds_read_b128 v[88:91], v217 offset:320
	ds_read_b128 v[72:75], v217 offset:448
	ds_read_b128 v[92:95], v217 offset:352
	ds_read_b128 v[76:79], v217 offset:480
	s_add_i32 s4, s72, 0x4000
	s_cmpk_lg_u32 s72, 0x8000
	s_cselect_b32 s90, s4, 0
	s_cmp_ge_u32 s71, s93
	s_cselect_b64 s[86:87], -1, 0
	s_and_b64 vcc, exec, s[86:87]
	s_cbranch_vccnz .LBB0_535
	s_add_i32 s4, s70, s90
	v_lshl_add_u64 v[156:157], v[156:157], 0, s[74:75]
	s_add_i32 m0, s4, 0xc000
	s_add_i32 s4, s4, 0xc400
	v_lshl_add_u64 v[158:159], v[158:159], 0, s[74:75]
	global_load_lds_dwordx4 v[156:157], off
	s_mov_b32 m0, s4
	s_nop 0
	global_load_lds_dwordx4 v[158:159], off

; #define LAS __attribute__((address_space(3)))
; __device__ __forceinline__ void finishSM(f32x16& p0, f32x16& p1, float alpha, float& l_reg, bf16x8& pa0, bf16x8& pa1, bf16x8& pa2, bf16x8& pa3) {
; #pragma unroll
;     for (int r = 0; r < 16; ++r) p1[r] = __builtin_amdgcn_exp2f(p1[r]);
;     float ps = 0;
; #pragma unroll
;     for (int r = 0; r < 16; ++r) ps += p0[r];
; #pragma unroll
;     for (int r = 0; r < 16; ++r) ps += p1[r];
;     { auto rr = __builtin_amdgcn_permlane32_swap(__float_as_uint(ps), __float_as_uint(ps), false, false);
;       ps = __uint_as_float(rr[0]) + __uint_as_float(rr[1]); }
;     l_reg = l_reg * alpha + ps;
;     ...
;     PK4(p0, 0, pa0); PK4(p0, 8, pa1); PK4(p1, 0, pa2); PK4(p1, 8, pa3);
;     ...
; }
; __device__ __forceinline__ void qkt(f32x16& p0, f32x16& p1, const char* Kslot, int r32, int hi, const bf16x8* qr, const LAS f32x4* cp) {
; #pragma unroll
;     for (int g = 0; g < 4; ++g) { const f32x4 c0 = cp[2 * g], c1 = cp[8 + 2 * g];
; #pragma unroll
;         for (int j = 0; j < 4; ++j) { p0[4 * g + j] = c0[j]; p1[4 * g + j] = c1[j]; } }
;     const char* kb[4];
; #pragma unroll
;     for (int dd = 0; dd < 4; ++dd) kb[dd] = Kslot + KSWZ(r32, (dd * 16 + hi * 8) * 2);
; #pragma unroll
;     for (int d0 = 0; d0 < 8; ++d0) { const char* a = kb[d0 & 3] + (d0 >> 2) * 128;
;         bf16x8 b0 = *reinterpret_cast<const bf16x8*>(a);
;         bf16x8 b1 = *reinterpret_cast<const bf16x8*>(a + 32 * 256);
;         p0 = __builtin_amdgcn_mfma_f32_32x32x16_bf16(b0, qr[d0], p0, 0, 0, 0);
;         p1 = __builtin_amdgcn_mfma_f32_32x32x16_bf16(b1, qr[d0], p1, 0, 0, 0); }
.LBB0_537:
	ds_read_b128 v[156:159], v237 offset:49152
	ds_read_b128 v[160:163], v237 offset:57344
	v_add_u32_e32 v238, s2, v194
	v_add_u32_e32 v239, s2, v195
	s_waitcnt lgkmcnt(0)
	v_mfma_f32_32x32x16_bf16 v[80:95], v[156:159], v[96:99], v[80:95]
	v_add_u32_e32 v240, s2, v196
	v_exp_f32_e32 v167, v167
	v_exp_f32_e32 v168, v168
	v_exp_f32_e32 v169, v169
	v_exp_f32_e32 v170, v170
	v_exp_f32_e32 v171, v171
	v_exp_f32_e32 v172, v172
	v_mfma_f32_32x32x16_bf16 v[64:79], v[160:163], v[96:99], v[64:79]
	ds_read_b128 v[156:159], v238 offset:49152
	ds_read_b128 v[160:163], v238 offset:57344
	v_exp_f32_e32 v173, v173
	v_exp_f32_e32 v174, v174
	v_exp_f32_e32 v175, v175
	v_exp_f32_e32 v176, v176
	v_exp_f32_e32 v234, v234
	v_exp_f32_e32 v235, v235
	s_waitcnt lgkmcnt(0)
	v_mfma_f32_32x32x16_bf16 v[80:95], v[156:159], v[100:103], v[80:95]
	v_exp_f32_e32 v236, v236
	v_mfma_f32_32x32x16_bf16 v[64:79], v[160:163], v[100:103], v[64:79]
	ds_read_b128 v[156:159], v239 offset:49152
	ds_read_b128 v[160:163], v239 offset:57344
	s_waitcnt lgkmcnt(0)
	v_mfma_f32_32x32x16_bf16 v[80:95], v[156:159], v[104:107], v[80:95]
	v_mfma_f32_32x32x16_bf16 v[64:79], v[160:163], v[104:107], v[64:79]
	ds_read_b128 v[156:159], v240 offset:49152
	ds_read_b128 v[160:163], v240 offset:57344
	s_waitcnt lgkmcnt(0)
	v_mfma_f32_32x32x16_bf16 v[80:95], v[156:159], v[108:111], v[80:95]
	v_mfma_f32_32x32x16_bf16 v[64:79], v[160:163], v[108:111], v[64:79]
	v_xor_b32_e32 v249, 0x80, v237
	v_xor_b32_e32 v250, 0x80, v238
	v_xor_b32_e32 v251, 0x80, v239
	v_xor_b32_e32 v252, 0x80, v240
	ds_read_b128 v[156:159], v249 offset:49152
	ds_read_b128 v[160:163], v249 offset:57344
	v_exp_f32_e32 v237, v164
	s_waitcnt lgkmcnt(0)
	v_mfma_f32_32x32x16_bf16 v[80:95], v[156:159], v[112:115], v[80:95]
	v_mfma_f32_32x32x16_bf16 v[64:79], v[160:163], v[112:115], v[64:79]
	ds_read_b128 v[156:159], v250 offset:49152
	ds_read_b128 v[160:163], v250 offset:57344
	v_exp_f32_e32 v238, v165
	s_waitcnt lgkmcnt(0)
	v_mfma_f32_32x32x16_bf16 v[80:95], v[156:159], v[116:119], v[80:95]
	v_mfma_f32_32x32x16_bf16 v[64:79], v[160:163], v[116:119], v[64:79]
	ds_read_b128 v[156:159], v251 offset:49152
	ds_read_b128 v[160:163], v251 offset:57344
	v_exp_f32_e32 v239, v166
	s_waitcnt lgkmcnt(0)
	v_mfma_f32_32x32x16_bf16 v[80:95], v[156:159], v[120:123], v[80:95]
	v_mfma_f32_32x32x16_bf16 v[64:79], v[160:163], v[120:123], v[64:79]
	ds_read_b128 v[156:159], v252 offset:49152
	ds_read_b128 v[160:163], v252 offset:57344
	s_waitcnt lgkmcnt(0)
	v_mfma_f32_32x32x16_bf16 v[80:95], v[156:159], v[124:127], v[80:95]
	v_add_f32_e32 v156, 0, v177
	v_add_f32_e32 v156, v178, v156
	v_add_f32_e32 v156, v179, v156
	v_add_f32_e32 v156, v221, v156
	v_add_f32_e32 v156, v222, v156
	v_add_f32_e32 v156, v223, v156
	v_add_f32_e32 v156, v224, v156
	v_add_f32_e32 v156, v225, v156
	v_add_f32_e32 v156, v226, v156
	v_add_f32_e32 v156, v227, v156
	v_add_f32_e32 v156, v228, v156
	v_add_f32_e32 v156, v229, v156
	v_add_f32_e32 v156, v230, v156
	v_add_f32_e32 v156, v231, v156
	v_add_f32_e32 v156, v232, v156
	v_add_f32_e32 v156, v233, v156
	v_add_f32_e32 v156, v237, v156
	v_add_f32_e32 v156, v238, v156
	v_add_f32_e32 v156, v239, v156
	v_add_f32_e32 v156, v167, v156
	v_add_f32_e32 v156, v168, v156
	v_add_f32_e32 v156, v169, v156
	v_add_f32_e32 v156, v170, v156
	v_add_f32_e32 v156, v171, v156
	v_add_f32_e32 v156, v172, v156
	v_add_f32_e32 v156, v173, v156
	v_mfma_f32_32x32x16_bf16 v[64:79], v[160:163], v[124:127], v[64:79]
	v_add_f32_e32 v156, v174, v156
	v_add_f32_e32 v156, v175, v156
	v_add_f32_e32 v156, v176, v156
	v_add_f32_e32 v156, v234, v156
	v_add_f32_e32 v156, v235, v156
	v_add_f32_e32 v156, v236, v156
	v_mov_b32_e32 v157, v156
	s_nop 1
	v_permlane32_swap_b32_e32 v156, v157
	v_cvt_pk_bf16_f32 v158, v177, v178
	v_cvt_pk_bf16_f32 v159, v179, v221
	v_cvt_pk_bf16_f32 v160, v222, v223
	v_cvt_pk_bf16_f32 v161, v224, v225
	v_cvt_pk_bf16_f32 v162, v226, v227
	v_cvt_pk_bf16_f32 v163, v228, v229
	v_cvt_pk_bf16_f32 v164, v230, v231
	v_cvt_pk_bf16_f32 v165, v232, v233
	v_cvt_pk_bf16_f32 v166, v237, v238
	v_cvt_pk_bf16_f32 v167, v239, v167
	v_cvt_pk_bf16_f32 v168, v168, v169
	v_cvt_pk_bf16_f32 v169, v170, v171
	v_cvt_pk_bf16_f32 v170, v172, v173
	v_cvt_pk_bf16_f32 v171, v174, v175
	v_cvt_pk_bf16_f32 v172, v176, v234
	v_cvt_pk_bf16_f32 v173, v235, v236
	s_nop 0
	v_permlane32_swap_b32_e32 v158, v160
	v_permlane32_swap_b32_e32 v159, v161
	v_permlane32_swap_b32_e32 v162, v164
	v_permlane32_swap_b32_e32 v163, v165
	v_permlane32_swap_b32_e32 v166, v168
	v_permlane32_swap_b32_e32 v167, v169
	v_permlane32_swap_b32_e32 v170, v172
	v_permlane32_swap_b32_e32 v171, v173
	v_add_u32_e32 v178, s73, v192
	s_cmp_le_i32 s92, s91
	s_cbranch_scc0 .Lband_1
; #define SBAR() __builtin_amdgcn_sched_barrier(0)
; #define PV_RD(d0, kh, X) do { constexpr int b_ = v_rd_off(d0, 2 * (kh), 0); TRRD(X##l0, b_); TRRD(X##h0, b_ + 2048); TRRD(X##l1, b_ + 4096); TRRD(X##h1, b_ + 6144); } while (0)
; #define PV_MM(d0, X, PA, PB) do { \
;         o[d0] = __builtin_amdgcn_mfma_f32_32x32x16_bf16(PA, (bf16x8){X##l0[0], X##l0[1], X##l0[2], X##l0[3], X##h0[0], X##h0[1], X##h0[2], X##h0[3]}, o[d0], 0, 0, 0);   \
;         o[d0] = __builtin_amdgcn_mfma_f32_32x32x16_bf16(PB, (bf16x8){X##l1[0], X##l1[1], X##l1[2], X##l1[3], X##h1[0], X##h1[1], X##h1[2], X##h1[3]}, o[d0], 0, 0, 0); } while (0)
; #define PV_W4() do { asm volatile("s_waitcnt lgkmcnt(4)" ::: "memory"); SBAR(); } while (0)
; #define PV_W0() do { asm volatile("s_waitcnt lgkmcnt(0)" ::: "memory"); SBAR(); } while (0)
; __device__ __forceinline__ void partialSM(f32x16& p0, f32x16& p1, float& m_reg, float& mn, float& alpha) {
;     float pmax = p0[0];
; #pragma unroll
;     for (int r = 1; r < 16; ++r) pmax = fmaxf(pmax, p0[r]);
; #pragma unroll
;     for (int r = 0; r < 16; ++r) pmax = fmaxf(pmax, p1[r]);
;     { auto rr = __builtin_amdgcn_permlane32_swap(__float_as_uint(pmax), __float_as_uint(pmax), false, false);
;       pmax = fmaxf(__uint_as_float(rr[0]), __uint_as_float(rr[1])); }
;     if (__builtin_expect(__all((pmax - m_reg) <= THR2), 1)) { mn = m_reg; alpha = 1.f; }
;     else { mn = fmaxf(m_reg, pmax); alpha = __builtin_amdgcn_exp2f(m_reg - mn); m_reg = mn; }
; __device__ __forceinline__ void pv_tile(f32x16* o, int vb0, bf16x8 pa0, bf16x8 pa1, bf16x8 pa2, bf16x8 pa3) {
;     ...
;     s16x4 al0, al1, ah0, ah1, bl0, bl1, bh0, bh1;
;     PV_RD(0, 0, a);
;     PV_RD(0, 1, b); PV_W4(); PV_MM(0, a, pa0, pa1); SBAR();
;     PV_RD(1, 0, a); PV_W4(); PV_MM(0, b, pa2, pa3); SBAR();
;     PV_RD(1, 1, b); PV_W4(); PV_MM(1, a, pa0, pa1); SBAR();
;     PV_RD(2, 0, a); PV_W4(); PV_MM(1, b, pa2, pa3); SBAR();
;     PV_RD(2, 1, b); PV_W4(); PV_MM(2, a, pa0, pa1); SBAR();
;     PV_RD(3, 0, a); PV_W4(); PV_MM(2, b, pa2, pa3); SBAR();
;     PV_RD(3, 1, b); PV_W4(); PV_MM(3, a, pa0, pa1); SBAR();
;     PV_W0(); PV_MM(3, b, pa2, pa3);
	ds_read_b64_tr_b16 v[174:175], v178 offset:0
	ds_read_b64_tr_b16 v[176:177], v178 offset:0x800
	ds_read_b64_tr_b16 v[222:223], v178 offset:0x1000
	ds_read_b64_tr_b16 v[224:225], v178 offset:0x1800
	ds_read_b64_tr_b16 v[226:227], v178 offset:0x2000
	ds_read_b64_tr_b16 v[228:229], v178 offset:0x2800
	ds_read_b64_tr_b16 v[230:231], v178 offset:0x3000
	ds_read_b64_tr_b16 v[232:233], v178 offset:0x3800
	s_waitcnt lgkmcnt(4)
	s_nop 0
	v_mfma_f32_32x32x16_bf16 v[48:63], v[158:161], v[174:177], v[48:63]
	v_max_f32_e32 v253, v81, v81
	v_max_f32_e32 v254, v80, v80
	v_mfma_f32_32x32x16_bf16 v[48:63], v[162:165], v[222:225], v[48:63]
	v_max_f32_e32 v253, v254, v253
	v_max3_f32 v253, v253, v82, v83
	ds_read_b64_tr_b16 v[174:175], v178 offset:0x200
	ds_read_b64_tr_b16 v[176:177], v178 offset:0xa00
	ds_read_b64_tr_b16 v[222:223], v178 offset:0x1200
	ds_read_b64_tr_b16 v[224:225], v178 offset:0x1a00
	s_waitcnt lgkmcnt(4)
	v_mfma_f32_32x32x16_bf16 v[48:63], v[166:169], v[226:229], v[48:63]
	v_max3_f32 v253, v253, v84, v85
	v_max3_f32 v253, v253, v86, v87
	v_mfma_f32_32x32x16_bf16 v[48:63], v[170:173], v[230:233], v[48:63]
	v_max3_f32 v253, v253, v88, v89
	v_max3_f32 v253, v253, v90, v91
	ds_read_b64_tr_b16 v[226:227], v178 offset:0x2200
	ds_read_b64_tr_b16 v[228:229], v178 offset:0x2a00
	ds_read_b64_tr_b16 v[230:231], v178 offset:0x3200
	ds_read_b64_tr_b16 v[232:233], v178 offset:0x3a00
	s_waitcnt lgkmcnt(4)
	v_mfma_f32_32x32x16_bf16 v[32:47], v[158:161], v[174:177], v[32:47]
	v_max3_f32 v253, v253, v92, v93
	v_max3_f32 v253, v253, v94, v95
	v_mfma_f32_32x32x16_bf16 v[32:47], v[162:165], v[222:225], v[32:47]
	v_max3_f32 v253, v253, v64, v65
	v_max3_f32 v253, v253, v66, v67
	ds_read_b64_tr_b16 v[174:175], v178 offset:0x400
	ds_read_b64_tr_b16 v[176:177], v178 offset:0xc00
	ds_read_b64_tr_b16 v[222:223], v178 offset:0x1400
	ds_read_b64_tr_b16 v[224:225], v178 offset:0x1c00
	s_waitcnt lgkmcnt(4)
	v_mfma_f32_32x32x16_bf16 v[32:47], v[166:169], v[226:229], v[32:47]
	v_max3_f32 v253, v253, v68, v69
	v_max3_f32 v253, v253, v70, v71
	v_mfma_f32_32x32x16_bf16 v[32:47], v[170:173], v[230:233], v[32:47]
	v_max3_f32 v253, v253, v72, v73
	v_max3_f32 v253, v253, v74, v75
	ds_read_b64_tr_b16 v[226:227], v178 offset:0x2400
	ds_read_b64_tr_b16 v[228:229], v178 offset:0x2c00
	ds_read_b64_tr_b16 v[230:231], v178 offset:0x3400
	ds_read_b64_tr_b16 v[232:233], v178 offset:0x3c00
	s_waitcnt lgkmcnt(4)
	v_mfma_f32_32x32x16_bf16 v[16:31], v[158:161], v[174:177], v[16:31]
	v_max3_f32 v253, v253, v76, v77
	v_max3_f32 v253, v253, v78, v79
	v_mfma_f32_32x32x16_bf16 v[16:31], v[162:165], v[222:225], v[16:31]
	v_mov_b32_e32 v254, v253
	s_nop 1
	ds_read_b64_tr_b16 v[174:175], v178 offset:0x600
	ds_read_b64_tr_b16 v[176:177], v178 offset:0xe00
	ds_read_b64_tr_b16 v[222:223], v178 offset:0x1600
	ds_read_b64_tr_b16 v[224:225], v178 offset:0x1e00
	s_waitcnt lgkmcnt(4)
	v_mfma_f32_32x32x16_bf16 v[16:31], v[166:169], v[226:229], v[16:31]
	v_permlane32_swap_b32_e32 v253, v254
	v_max_f32_e32 v254, v254, v254
	v_mfma_f32_32x32x16_bf16 v[16:31], v[170:173], v[230:233], v[16:31]
	v_max_f32_e32 v253, v253, v253
	v_max_f32_e32 v253, v253, v254
	ds_read_b64_tr_b16 v[226:227], v178 offset:0x2600
	ds_read_b64_tr_b16 v[228:229], v178 offset:0x2e00
	ds_read_b64_tr_b16 v[230:231], v178 offset:0x3600
	ds_read_b64_tr_b16 v[232:233], v178 offset:0x3e00
	s_waitcnt lgkmcnt(4)
	v_mfma_f32_32x32x16_bf16 v[0:15], v[158:161], v[174:177], v[0:15]
	v_sub_f32_e32 v254, v253, v154
	v_cmp_ge_f32_e32 vcc, s33, v254
	v_mfma_f32_32x32x16_bf16 v[0:15], v[162:165], v[222:225], v[0:15]
	v_max_f32_e32 v254, v154, v154
	v_max_f32_e32 v254, v254, v253
	s_waitcnt lgkmcnt(0)
	v_mfma_f32_32x32x16_bf16 v[0:15], v[166:169], v[226:229], v[0:15]
	v_sub_f32_e32 v253, v154, v254
	v_exp_f32_e32 v253, v253
	v_mfma_f32_32x32x16_bf16 v[0:15], v[170:173], v[230:233], v[0:15]
	v_mov_b32_e32 v158, v253
	v_mov_b32_e32 v159, v254
	s_branch .Lmaxtail_1

; #define LAS __attribute__((address_space(3)))
; __device__ __forceinline__ void qkt(f32x16& p0, f32x16& p1, const char* Kslot, int r32, int hi, const bf16x8* qr, const LAS f32x4* cp) {
; #pragma unroll
;     for (int g = 0; g < 4; ++g) { const f32x4 c0 = cp[2 * g], c1 = cp[8 + 2 * g];
; #pragma unroll
;         for (int j = 0; j < 4; ++j) { p0[4 * g + j] = c0[j]; p1[4 * g + j] = c1[j]; } }
.LBB0_568:
	s_add_i32 s2, s90, 0
	v_add_u32_e32 v212, s2, v193
	ds_read_b128 v[80:83], v197 offset:256
	ds_read_b128 v[84:87], v197 offset:288
	ds_read_b128 v[64:67], v197 offset:384
	ds_read_b128 v[68:71], v197 offset:416
	ds_read_b128 v[88:91], v197 offset:320
	ds_read_b128 v[72:75], v197 offset:448
	ds_read_b128 v[92:95], v197 offset:352
	ds_read_b128 v[76:79], v197 offset:480
	s_add_i32 s4, s72, 0x4000
	s_cmpk_lg_u32 s72, 0x8000
	s_cselect_b32 s92, s4, 0
	s_cmp_ge_u32 s87, s89
	s_cselect_b64 s[76:77], -1, 0
	s_and_b64 vcc, exec, s[76:77]
	s_cbranch_vccnz .LBB0_570
	s_add_i32 s4, s86, s92
	v_lshl_add_u64 v[146:147], v[146:147], 0, s[74:75]
	s_add_i32 m0, s4, 0xc000
	s_add_i32 s4, s4, 0xc400
	v_lshl_add_u64 v[148:149], v[148:149], 0, s[74:75]
	global_load_lds_dwordx4 v[146:147], off
	s_mov_b32 m0, s4
	s_nop 0
	global_load_lds_dwordx4 v[148:149], off

; #define LAS __attribute__((address_space(3)))
; __device__ __forceinline__ void finishSM(f32x16& p0, f32x16& p1, float alpha, float& l_reg, bf16x8& pa0, bf16x8& pa1, bf16x8& pa2, bf16x8& pa3) {
; #pragma unroll
;     for (int r = 0; r < 16; ++r) p1[r] = __builtin_amdgcn_exp2f(p1[r]);
;     float ps = 0;
; #pragma unroll
;     for (int r = 0; r < 16; ++r) ps += p0[r];
; #pragma unroll
;     for (int r = 0; r < 16; ++r) ps += p1[r];
;     { auto rr = __builtin_amdgcn_permlane32_swap(__float_as_uint(ps), __float_as_uint(ps), false, false);
;       ps = __uint_as_float(rr[0]) + __uint_as_float(rr[1]); }
;     l_reg = l_reg * alpha + ps;
;     ...
;     PK4(p0, 0, pa0); PK4(p0, 8, pa1); PK4(p1, 0, pa2); PK4(p1, 8, pa3);
;     ...
; }
; __device__ __forceinline__ void qkt(f32x16& p0, f32x16& p1, const char* Kslot, int r32, int hi, const bf16x8* qr, const LAS f32x4* cp) {
; #pragma unroll
;     for (int g = 0; g < 4; ++g) { const f32x4 c0 = cp[2 * g], c1 = cp[8 + 2 * g];
; #pragma unroll
;         for (int j = 0; j < 4; ++j) { p0[4 * g + j] = c0[j]; p1[4 * g + j] = c1[j]; } }
;     const char* kb[4];
; #pragma unroll
;     for (int dd = 0; dd < 4; ++dd) kb[dd] = Kslot + KSWZ(r32, (dd * 16 + hi * 8) * 2);
; #pragma unroll
;     for (int d0 = 0; d0 < 8; ++d0) { const char* a = kb[d0 & 3] + (d0 >> 2) * 128;
;         bf16x8 b0 = *reinterpret_cast<const bf16x8*>(a);
;         bf16x8 b1 = *reinterpret_cast<const bf16x8*>(a + 32 * 256);
;         p0 = __builtin_amdgcn_mfma_f32_32x32x16_bf16(b0, qr[d0], p0, 0, 0, 0);
;         p1 = __builtin_amdgcn_mfma_f32_32x32x16_bf16(b1, qr[d0], p1, 0, 0, 0); }
.LBB0_572:
	ds_read_b128 v[146:149], v212 offset:49152
	ds_read_b128 v[150:153], v212 offset:57344
	v_add_u32_e32 v213, s2, v194
	v_add_u32_e32 v214, s2, v195
	s_waitcnt lgkmcnt(0)
	v_mfma_f32_32x32x16_bf16 v[80:95], v[146:149], v[96:99], v[80:95]
	v_add_u32_e32 v215, s2, v196
	v_exp_f32_e32 v157, v157
	v_exp_f32_e32 v158, v158
	v_exp_f32_e32 v159, v159
	v_exp_f32_e32 v160, v160
	v_exp_f32_e32 v161, v161
	v_exp_f32_e32 v162, v162
	v_mfma_f32_32x32x16_bf16 v[64:79], v[150:153], v[96:99], v[64:79]
	ds_read_b128 v[146:149], v213 offset:49152
	ds_read_b128 v[150:153], v213 offset:57344
	v_exp_f32_e32 v163, v163
	v_exp_f32_e32 v164, v164
	v_exp_f32_e32 v165, v165
	v_exp_f32_e32 v166, v166
	v_exp_f32_e32 v209, v209
	v_exp_f32_e32 v210, v210
	s_waitcnt lgkmcnt(0)
	v_mfma_f32_32x32x16_bf16 v[80:95], v[146:149], v[100:103], v[80:95]
	v_exp_f32_e32 v211, v211
	v_mfma_f32_32x32x16_bf16 v[64:79], v[150:153], v[100:103], v[64:79]
	ds_read_b128 v[146:149], v214 offset:49152
	ds_read_b128 v[150:153], v214 offset:57344
	s_waitcnt lgkmcnt(0)
	v_mfma_f32_32x32x16_bf16 v[80:95], v[146:149], v[104:107], v[80:95]
	v_mfma_f32_32x32x16_bf16 v[64:79], v[150:153], v[104:107], v[64:79]
	ds_read_b128 v[146:149], v215 offset:49152
	ds_read_b128 v[150:153], v215 offset:57344
	s_waitcnt lgkmcnt(0)
	v_mfma_f32_32x32x16_bf16 v[80:95], v[146:149], v[108:111], v[80:95]
	v_mfma_f32_32x32x16_bf16 v[64:79], v[150:153], v[108:111], v[64:79]
	v_xor_b32_e32 v249, 0x80, v212
	v_xor_b32_e32 v250, 0x80, v213
	v_xor_b32_e32 v251, 0x80, v214
	v_xor_b32_e32 v252, 0x80, v215
	ds_read_b128 v[146:149], v249 offset:49152
	ds_read_b128 v[150:153], v249 offset:57344
	v_exp_f32_e32 v212, v154
	s_waitcnt lgkmcnt(0)
	v_mfma_f32_32x32x16_bf16 v[80:95], v[146:149], v[112:115], v[80:95]
	v_mfma_f32_32x32x16_bf16 v[64:79], v[150:153], v[112:115], v[64:79]
	ds_read_b128 v[146:149], v250 offset:49152
	ds_read_b128 v[150:153], v250 offset:57344
	v_exp_f32_e32 v213, v155
	s_waitcnt lgkmcnt(0)
	v_mfma_f32_32x32x16_bf16 v[80:95], v[146:149], v[116:119], v[80:95]
	v_mfma_f32_32x32x16_bf16 v[64:79], v[150:153], v[116:119], v[64:79]
	ds_read_b128 v[146:149], v251 offset:49152
	ds_read_b128 v[150:153], v251 offset:57344
	v_exp_f32_e32 v214, v156
	s_waitcnt lgkmcnt(0)
	v_mfma_f32_32x32x16_bf16 v[80:95], v[146:149], v[120:123], v[80:95]
	v_mfma_f32_32x32x16_bf16 v[64:79], v[150:153], v[120:123], v[64:79]
	ds_read_b128 v[146:149], v252 offset:49152
	ds_read_b128 v[150:153], v252 offset:57344
	s_waitcnt lgkmcnt(0)
	v_mfma_f32_32x32x16_bf16 v[80:95], v[146:149], v[124:127], v[80:95]
	v_add_f32_e32 v146, 0, v167
	v_add_f32_e32 v146, v168, v146
	v_add_f32_e32 v146, v169, v146
	v_add_f32_e32 v146, v178, v146
	v_add_f32_e32 v146, v179, v146
	v_add_f32_e32 v146, v198, v146
	v_add_f32_e32 v146, v199, v146
	v_add_f32_e32 v146, v200, v146
	v_add_f32_e32 v146, v201, v146
	v_add_f32_e32 v146, v202, v146
	v_add_f32_e32 v146, v203, v146
	v_add_f32_e32 v146, v204, v146
	v_add_f32_e32 v146, v205, v146
	v_add_f32_e32 v146, v206, v146
	v_add_f32_e32 v146, v207, v146
	v_add_f32_e32 v146, v208, v146
	v_add_f32_e32 v146, v212, v146
	v_add_f32_e32 v146, v213, v146
	v_add_f32_e32 v146, v214, v146
	v_add_f32_e32 v146, v157, v146
	v_add_f32_e32 v146, v158, v146
	v_add_f32_e32 v146, v159, v146
	v_add_f32_e32 v146, v160, v146
	v_add_f32_e32 v146, v161, v146
	v_add_f32_e32 v146, v162, v146
	v_add_f32_e32 v146, v163, v146
	v_mfma_f32_32x32x16_bf16 v[64:79], v[150:153], v[124:127], v[64:79]
	v_add_f32_e32 v146, v164, v146
	v_add_f32_e32 v146, v165, v146
	v_add_f32_e32 v146, v166, v146
	v_add_f32_e32 v146, v209, v146
	v_add_f32_e32 v146, v210, v146
	v_add_f32_e32 v146, v211, v146
	v_mov_b32_e32 v147, v146
	s_nop 1
	v_permlane32_swap_b32_e32 v146, v147
	v_cvt_pk_bf16_f32 v148, v167, v168
	v_cvt_pk_bf16_f32 v149, v169, v178
	v_cvt_pk_bf16_f32 v150, v179, v198
	v_cvt_pk_bf16_f32 v151, v199, v200
	v_cvt_pk_bf16_f32 v152, v201, v202
	v_cvt_pk_bf16_f32 v153, v203, v204
	v_cvt_pk_bf16_f32 v154, v205, v206
	v_cvt_pk_bf16_f32 v155, v207, v208
	v_cvt_pk_bf16_f32 v156, v212, v213
	v_cvt_pk_bf16_f32 v157, v214, v157
	v_cvt_pk_bf16_f32 v158, v158, v159
	v_cvt_pk_bf16_f32 v159, v160, v161
	v_cvt_pk_bf16_f32 v160, v162, v163
	v_cvt_pk_bf16_f32 v161, v164, v165
	v_cvt_pk_bf16_f32 v162, v166, v209
	v_cvt_pk_bf16_f32 v163, v210, v211
	s_nop 0
	v_permlane32_swap_b32_e32 v148, v150
	v_permlane32_swap_b32_e32 v149, v151
	v_permlane32_swap_b32_e32 v152, v154
	v_permlane32_swap_b32_e32 v153, v155
	v_permlane32_swap_b32_e32 v156, v158
	v_permlane32_swap_b32_e32 v157, v159
	v_permlane32_swap_b32_e32 v160, v162
	v_permlane32_swap_b32_e32 v161, v163
	v_add_u32_e32 v168, s73, v192
	s_cmp_le_i32 s91, s88
	s_cbranch_scc0 .Lband_3
; #define SBAR() __builtin_amdgcn_sched_barrier(0)
; #define PV_RD(d0, kh, X) do { constexpr int b_ = v_rd_off(d0, 2 * (kh), 0); TRRD(X##l0, b_); TRRD(X##h0, b_ + 2048); TRRD(X##l1, b_ + 4096); TRRD(X##h1, b_ + 6144); } while (0)
; #define PV_MM(d0, X, PA, PB) do { \
;         o[d0] = __builtin_amdgcn_mfma_f32_32x32x16_bf16(PA, (bf16x8){X##l0[0], X##l0[1], X##l0[2], X##l0[3], X##h0[0], X##h0[1], X##h0[2], X##h0[3]}, o[d0], 0, 0, 0);   \
;         o[d0] = __builtin_amdgcn_mfma_f32_32x32x16_bf16(PB, (bf16x8){X##l1[0], X##l1[1], X##l1[2], X##l1[3], X##h1[0], X##h1[1], X##h1[2], X##h1[3]}, o[d0], 0, 0, 0); } while (0)
; #define PV_W4() do { asm volatile("s_waitcnt lgkmcnt(4)" ::: "memory"); SBAR(); } while (0)
; #define PV_W0() do { asm volatile("s_waitcnt lgkmcnt(0)" ::: "memory"); SBAR(); } while (0)
; __device__ __forceinline__ void partialSM(f32x16& p0, f32x16& p1, float& m_reg, float& mn, float& alpha) {
;     float pmax = p0[0];
; #pragma unroll
;     for (int r = 1; r < 16; ++r) pmax = fmaxf(pmax, p0[r]);
; #pragma unroll
;     for (int r = 0; r < 16; ++r) pmax = fmaxf(pmax, p1[r]);
;     { auto rr = __builtin_amdgcn_permlane32_swap(__float_as_uint(pmax), __float_as_uint(pmax), false, false);
;       pmax = fmaxf(__uint_as_float(rr[0]), __uint_as_float(rr[1])); }
;     if (__builtin_expect(__all((pmax - m_reg) <= THR2), 1)) { mn = m_reg; alpha = 1.f; }
;     else { mn = fmaxf(m_reg, pmax); alpha = __builtin_amdgcn_exp2f(m_reg - mn); m_reg = mn; }
; __device__ __forceinline__ void pv_tile(f32x16* o, int vb0, bf16x8 pa0, bf16x8 pa1, bf16x8 pa2, bf16x8 pa3) {
;     ...
;     s16x4 al0, al1, ah0, ah1, bl0, bl1, bh0, bh1;
;     PV_RD(0, 0, a);
;     PV_RD(0, 1, b); PV_W4(); PV_MM(0, a, pa0, pa1); SBAR();
;     PV_RD(1, 0, a); PV_W4(); PV_MM(0, b, pa2, pa3); SBAR();
;     PV_RD(1, 1, b); PV_W4(); PV_MM(1, a, pa0, pa1); SBAR();
;     PV_RD(2, 0, a); PV_W4(); PV_MM(1, b, pa2, pa3); SBAR();
;     PV_RD(2, 1, b); PV_W4(); PV_MM(2, a, pa0, pa1); SBAR();
;     PV_RD(3, 0, a); PV_W4(); PV_MM(2, b, pa2, pa3); SBAR();
;     PV_RD(3, 1, b); PV_W4(); PV_MM(3, a, pa0, pa1); SBAR();
;     PV_W0(); PV_MM(3, b, pa2, pa3);
	ds_read_b64_tr_b16 v[164:165], v168 offset:0
	ds_read_b64_tr_b16 v[166:167], v168 offset:0x800
	ds_read_b64_tr_b16 v[198:199], v168 offset:0x1000
	ds_read_b64_tr_b16 v[200:201], v168 offset:0x1800
	ds_read_b64_tr_b16 v[202:203], v168 offset:0x2000
	ds_read_b64_tr_b16 v[204:205], v168 offset:0x2800
	ds_read_b64_tr_b16 v[206:207], v168 offset:0x3000
	ds_read_b64_tr_b16 v[208:209], v168 offset:0x3800
	s_waitcnt lgkmcnt(4)
	s_nop 0
	v_mfma_f32_32x32x16_bf16 v[48:63], v[148:151], v[164:167], v[48:63]
	v_max_f32_e32 v253, v81, v81
	v_max_f32_e32 v254, v80, v80
	v_mfma_f32_32x32x16_bf16 v[48:63], v[152:155], v[198:201], v[48:63]
	v_max_f32_e32 v253, v254, v253
	v_max3_f32 v253, v253, v82, v83
	ds_read_b64_tr_b16 v[164:165], v168 offset:0x200
	ds_read_b64_tr_b16 v[166:167], v168 offset:0xa00
	ds_read_b64_tr_b16 v[198:199], v168 offset:0x1200
	ds_read_b64_tr_b16 v[200:201], v168 offset:0x1a00
	s_waitcnt lgkmcnt(4)
	v_mfma_f32_32x32x16_bf16 v[48:63], v[156:159], v[202:205], v[48:63]
	v_max3_f32 v253, v253, v84, v85
	v_max3_f32 v253, v253, v86, v87
	v_mfma_f32_32x32x16_bf16 v[48:63], v[160:163], v[206:209], v[48:63]
	v_max3_f32 v253, v253, v88, v89
	v_max3_f32 v253, v253, v90, v91
	ds_read_b64_tr_b16 v[202:203], v168 offset:0x2200
	ds_read_b64_tr_b16 v[204:205], v168 offset:0x2a00
	ds_read_b64_tr_b16 v[206:207], v168 offset:0x3200
	ds_read_b64_tr_b16 v[208:209], v168 offset:0x3a00
	s_waitcnt lgkmcnt(4)
	v_mfma_f32_32x32x16_bf16 v[32:47], v[148:151], v[164:167], v[32:47]
	v_max3_f32 v253, v253, v92, v93
	v_max3_f32 v253, v253, v94, v95
	v_mfma_f32_32x32x16_bf16 v[32:47], v[152:155], v[198:201], v[32:47]
	v_max3_f32 v253, v253, v64, v65
	v_max3_f32 v253, v253, v66, v67
	ds_read_b64_tr_b16 v[164:165], v168 offset:0x400
	ds_read_b64_tr_b16 v[166:167], v168 offset:0xc00
	ds_read_b64_tr_b16 v[198:199], v168 offset:0x1400
	ds_read_b64_tr_b16 v[200:201], v168 offset:0x1c00
	s_waitcnt lgkmcnt(4)
	v_mfma_f32_32x32x16_bf16 v[32:47], v[156:159], v[202:205], v[32:47]
	v_max3_f32 v253, v253, v68, v69
	v_max3_f32 v253, v253, v70, v71
	v_mfma_f32_32x32x16_bf16 v[32:47], v[160:163], v[206:209], v[32:47]
	v_max3_f32 v253, v253, v72, v73
	v_max3_f32 v253, v253, v74, v75
	ds_read_b64_tr_b16 v[202:203], v168 offset:0x2400
	ds_read_b64_tr_b16 v[204:205], v168 offset:0x2c00
	ds_read_b64_tr_b16 v[206:207], v168 offset:0x3400
	ds_read_b64_tr_b16 v[208:209], v168 offset:0x3c00
	s_waitcnt lgkmcnt(4)
	v_mfma_f32_32x32x16_bf16 v[16:31], v[148:151], v[164:167], v[16:31]
	v_max3_f32 v253, v253, v76, v77
	v_max3_f32 v253, v253, v78, v79
	v_mfma_f32_32x32x16_bf16 v[16:31], v[152:155], v[198:201], v[16:31]
	v_mov_b32_e32 v254, v253
	s_nop 1
	ds_read_b64_tr_b16 v[164:165], v168 offset:0x600
	ds_read_b64_tr_b16 v[166:167], v168 offset:0xe00
	ds_read_b64_tr_b16 v[198:199], v168 offset:0x1600
	ds_read_b64_tr_b16 v[200:201], v168 offset:0x1e00
	s_waitcnt lgkmcnt(4)
	v_mfma_f32_32x32x16_bf16 v[16:31], v[156:159], v[202:205], v[16:31]
	v_permlane32_swap_b32_e32 v253, v254
	v_max_f32_e32 v254, v254, v254
	v_mfma_f32_32x32x16_bf16 v[16:31], v[160:163], v[206:209], v[16:31]
	v_max_f32_e32 v253, v253, v253
	v_max_f32_e32 v253, v253, v254
	ds_read_b64_tr_b16 v[202:203], v168 offset:0x2600
	ds_read_b64_tr_b16 v[204:205], v168 offset:0x2e00
	ds_read_b64_tr_b16 v[206:207], v168 offset:0x3600
	ds_read_b64_tr_b16 v[208:209], v168 offset:0x3e00
	s_waitcnt lgkmcnt(4)
	v_mfma_f32_32x32x16_bf16 v[0:15], v[148:151], v[164:167], v[0:15]
	v_sub_f32_e32 v254, v253, v144
	v_cmp_ge_f32_e32 vcc, s33, v254
	v_mfma_f32_32x32x16_bf16 v[0:15], v[152:155], v[198:201], v[0:15]
	v_max_f32_e32 v254, v144, v144
	v_max_f32_e32 v254, v254, v253
	s_waitcnt lgkmcnt(0)
	v_mfma_f32_32x32x16_bf16 v[0:15], v[156:159], v[202:205], v[0:15]
	v_sub_f32_e32 v253, v144, v254
	v_exp_f32_e32 v253, v253
	v_mfma_f32_32x32x16_bf16 v[0:15], v[160:163], v[206:209], v[0:15]
	v_mov_b32_e32 v148, v253
	v_mov_b32_e32 v149, v254
	s_branch .Lmaxtail_3
